# out-proj/down epilogue: residual tile loads issued two row-groups ahead (saddr form, private regs), counted vmcnt so stores stay in flight
# speedup vs baseline: 1.0039x; 1.0039x over previous
.LBB0_1164:
	v_lshl_add_u32 v138, s35, 8, v140
	v_lshl_or_b32 v136, s34, 8, v142
	v_readlane_b32 s76, v255, 6
	v_readlane_b32 s77, v255, 7
	v_lshl_add_u32 v230, v138, 10, v136
	v_lshlrev_b32_e32 v230, 2, v230
	s_nop 3
	global_load_dwordx4 v[164:167], v230, s[76:77]
	global_load_dwordx4 v[168:171], v230, s[76:77] offset:64
	global_load_dwordx4 v[172:175], v230, s[76:77] offset:512
	global_load_dwordx4 v[176:179], v230, s[76:77] offset:576
	v_add_u32_e32 v231, 0x10000, v230
	global_load_dwordx4 v[180:183], v231, s[76:77]
	global_load_dwordx4 v[184:187], v231, s[76:77] offset:64
	global_load_dwordx4 v[188:191], v231, s[76:77] offset:512
	global_load_dwordx4 v[226:229], v231, s[76:77] offset:576
	v_ashrrev_i32_e32 v139, 31, v138
	v_ashrrev_i32_e32 v137, 31, v136
	v_lshlrev_b64 v[144:145], 10, v[138:139]
	v_lshl_add_u64 v[148:149], v[144:145], 0, v[136:137]
	v_readlane_b32 s52, v255, 6
	v_lshlrev_b64 v[150:151], 2, v[148:149]
	v_readlane_b32 s53, v255, 7
	v_lshl_add_u64 v[154:155], v[148:149], 1, s[6:7]
	s_nop 0
	v_lshl_add_u64 v[152:153], s[52:53], 0, v[150:151]
	v_readlane_b32 s52, v254, 45
	v_readlane_b32 s58, v254, 51
	v_readlane_b32 s59, v254, 52
	v_readlane_b32 s53, v254, 46
	s_lshl_b32 s52, s34, 2
	v_lshl_add_u64 v[156:157], s[58:59], 0, v[150:151]
	v_readlane_b32 s54, v254, 47
	v_readlane_b32 s55, v254, 48
	s_ashr_i32 s53, s52, 31
	v_readlane_b32 s56, v254, 49
	v_readlane_b32 s57, v254, 50
	s_waitcnt vmcnt(7) lgkmcnt(0)
	v_pk_add_f32 v[128:129], v[128:129], v[166:167]
	v_pk_add_f32 v[126:127], v[126:127], v[164:165]
	v_cvt_pk_bf16_f32 v145, v128, v129
	v_cvt_pk_bf16_f32 v144, v126, v127
	global_store_dwordx4 v[156:157], v[126:129], off
	global_store_dwordx2 v[154:155], v[144:145], off
	s_waitcnt vmcnt(8) lgkmcnt(0)
	v_pk_add_f32 v[124:125], v[124:125], v[170:171]
	v_pk_add_f32 v[122:123], v[122:123], v[168:169]
	v_cvt_pk_bf16_f32 v145, v124, v125
	v_cvt_pk_bf16_f32 v144, v122, v123
	global_store_dwordx4 v[156:157], v[122:125], off offset:64
	global_store_dwordx2 v[154:155], v[144:145], off offset:32
	s_waitcnt vmcnt(9) lgkmcnt(0)
	v_pk_add_f32 v[146:147], v[120:121], v[174:175]
	v_pk_add_f32 v[144:145], v[118:119], v[172:173]
	v_cvt_pk_bf16_f32 v119, v146, v147
	v_cvt_pk_bf16_f32 v118, v144, v145
	global_store_dwordx4 v[156:157], v[144:147], off offset:512
	global_store_dwordx2 v[154:155], v[118:119], off offset:256
	v_mul_f32_e32 v120, v127, v127
	v_mul_f32_e32 v121, v129, v129
	v_fmac_f32_e32 v120, v126, v126
	v_fmac_f32_e32 v121, v128, v128
	v_add_f32_e32 v120, v120, v121
	v_mul_f32_e32 v121, v123, v123
	v_mul_f32_e32 v123, v125, v125
	v_fmac_f32_e32 v121, v122, v122
	v_fmac_f32_e32 v123, v124, v124
	v_add_f32_e32 v121, v121, v123
	v_add_f32_e32 v120, v120, v121
	v_mul_f32_e32 v121, v145, v145
	v_mul_f32_e32 v122, v147, v147
	v_fmac_f32_e32 v121, v144, v144
	v_fmac_f32_e32 v122, v146, v146
	v_add_f32_e32 v121, v121, v122
	v_and_b32_e32 v119, 64, v197
	v_add_f32_e32 v124, v120, v121
	v_xor_b32_e32 v118, 16, v197
	v_add_u32_e32 v119, 64, v119
	v_cmp_lt_i32_e32 vcc, v118, v119
	s_waitcnt vmcnt(10) lgkmcnt(0)
	v_pk_add_f32 v[122:123], v[116:117], v[178:179]
	v_pk_add_f32 v[120:121], v[114:115], v[176:177]
	v_add_u32_e32 v231, 0x20000, v230
	global_load_dwordx4 v[164:167], v231, s[76:77]
	global_load_dwordx4 v[168:171], v231, s[76:77] offset:64
	global_load_dwordx4 v[172:175], v231, s[76:77] offset:512
	global_load_dwordx4 v[176:179], v231, s[76:77] offset:576
	v_mul_f32_e32 v115, v123, v123
	v_mul_f32_e32 v114, v121, v121
	v_fmac_f32_e32 v114, v120, v120
	v_fmac_f32_e32 v115, v122, v122
	v_cndmask_b32_e32 v118, v197, v118, vcc
	v_add_f32_e32 v114, v114, v115
	v_lshlrev_b32_e32 v118, 2, v118
	v_add_f32_e32 v114, v124, v114
	ds_bpermute_b32 v115, v118, v114
	v_xor_b32_e32 v116, 32, v197
	v_cmp_lt_i32_e32 vcc, v116, v119
	global_store_dwordx4 v[156:157], v[120:123], off offset:576
	s_waitcnt lgkmcnt(0)
	v_add_f32_e32 v114, v114, v115
	v_cndmask_b32_e32 v116, v197, v116, vcc
	v_lshlrev_b32_e32 v116, 2, v116
	ds_bpermute_b32 v115, v116, v114
	v_cvt_pk_bf16_f32 v120, v120, v121
	v_cvt_pk_bf16_f32 v121, v122, v123
	global_store_dwordx2 v[154:155], v[120:121], off offset:288
	s_and_saveexec_b64 s[54:55], s[0:1]
	s_cbranch_execz .LBB0_1166
	v_readlane_b32 s34, v254, 43
	v_lshlrev_b64 v[120:121], 6, v[138:139]
	v_readlane_b32 s35, v254, 44
	v_lshl_add_u64 v[120:121], s[42:43], 0, v[120:121]
	s_mov_b32 s31, s35
	v_lshl_add_u64 v[120:121], s[52:53], 2, v[120:121]
	s_lshl_b32 s34, s64, 2
	v_writelane_b32 v254, s30, 43
	v_lshl_add_u64 v[120:121], v[120:121], 0, s[34:35]
	s_waitcnt lgkmcnt(0)
	v_add_f32_e32 v114, v114, v115
	v_writelane_b32 v254, s31, 44
	global_store_dword v[120:121], v114, off
.LBB0_1166:
	s_or_b64 exec, exec, s[54:55]
	v_or_b32_e32 v114, 16, v138
	s_waitcnt lgkmcnt(0)
	v_ashrrev_i32_e32 v115, 31, v114
	v_lshlrev_b64 v[120:121], 10, v[114:115]
	v_lshl_add_u64 v[124:125], v[120:121], 0, v[136:137]
	v_readlane_b32 s34, v255, 6
	v_lshlrev_b64 v[126:127], 2, v[124:125]
	v_readlane_b32 s35, v255, 7
	v_readlane_b32 s68, v254, 45
	v_readlane_b32 s74, v254, 51
	v_lshl_add_u64 v[128:129], s[34:35], 0, v[126:127]
	v_readlane_b32 s75, v254, 52
	v_lshl_add_u64 v[124:125], v[124:125], 1, s[6:7]
	v_readlane_b32 s69, v254, 46
	v_lshl_add_u64 v[126:127], s[74:75], 0, v[126:127]
	v_readlane_b32 s70, v254, 47
	v_readlane_b32 s71, v254, 48
	v_readlane_b32 s72, v254, 49
	v_readlane_b32 s73, v254, 50
	s_waitcnt vmcnt(15) lgkmcnt(0)
	v_pk_add_f32 v[112:113], v[112:113], v[182:183]
	v_pk_add_f32 v[110:111], v[110:111], v[180:181]
	v_cvt_pk_bf16_f32 v121, v112, v113
	v_cvt_pk_bf16_f32 v120, v110, v111
	global_store_dwordx4 v[126:127], v[110:113], off
	global_store_dwordx2 v[124:125], v[120:121], off
	v_mul_f32_e32 v111, v111, v111
	v_mul_f32_e32 v113, v113, v113
	v_fmac_f32_e32 v111, v110, v110
	v_fmac_f32_e32 v113, v112, v112
	v_add_f32_e32 v110, v111, v113
	s_waitcnt vmcnt(16) lgkmcnt(0)
	v_pk_add_f32 v[108:109], v[108:109], v[186:187]
	v_pk_add_f32 v[106:107], v[106:107], v[184:185]
	v_cvt_pk_bf16_f32 v121, v108, v109
	v_cvt_pk_bf16_f32 v120, v106, v107
	global_store_dwordx4 v[126:127], v[106:109], off offset:64
	global_store_dwordx2 v[124:125], v[120:121], off offset:32
	v_mul_f32_e32 v107, v107, v107
	v_mul_f32_e32 v109, v109, v109
	v_fmac_f32_e32 v107, v106, v106
	v_fmac_f32_e32 v109, v108, v108
	v_add_f32_e32 v106, v107, v109
	v_add_f32_e32 v106, v110, v106
	s_waitcnt vmcnt(17) lgkmcnt(0)
	v_pk_add_f32 v[104:105], v[104:105], v[190:191]
	v_pk_add_f32 v[102:103], v[102:103], v[188:189]
	v_cvt_pk_bf16_f32 v121, v104, v105
	v_cvt_pk_bf16_f32 v120, v102, v103
	global_store_dwordx4 v[126:127], v[102:105], off offset:512
	global_store_dwordx2 v[124:125], v[120:121], off offset:256
	v_mul_f32_e32 v103, v103, v103
	v_mul_f32_e32 v105, v105, v105
	v_fmac_f32_e32 v103, v102, v102
	v_fmac_f32_e32 v105, v104, v104
	v_add_f32_e32 v102, v103, v105
	v_add_f32_e32 v104, v106, v102
	s_waitcnt vmcnt(18) lgkmcnt(0)
	v_pk_add_f32 v[102:103], v[100:101], v[228:229]
	v_pk_add_f32 v[100:101], v[98:99], v[226:227]
	v_add_u32_e32 v231, 0x30000, v230
	global_load_dwordx4 v[180:183], v231, s[76:77]
	global_load_dwordx4 v[184:187], v231, s[76:77] offset:64
	global_load_dwordx4 v[188:191], v231, s[76:77] offset:512
	global_load_dwordx4 v[226:229], v231, s[76:77] offset:576
	v_mul_f32_e32 v99, v103, v103
	v_mul_f32_e32 v98, v101, v101
	v_fmac_f32_e32 v98, v100, v100
	v_fmac_f32_e32 v99, v102, v102
	v_add_f32_e32 v98, v98, v99
	v_add_f32_e32 v98, v104, v98
	ds_bpermute_b32 v99, v118, v98
	global_store_dwordx4 v[126:127], v[100:103], off offset:576
	s_waitcnt lgkmcnt(0)
	v_add_f32_e32 v98, v98, v99
	ds_bpermute_b32 v99, v116, v98
	v_cvt_pk_bf16_f32 v100, v100, v101
	v_cvt_pk_bf16_f32 v101, v102, v103
	global_store_dwordx2 v[124:125], v[100:101], off offset:288
	s_and_saveexec_b64 s[54:55], s[0:1]
	s_cbranch_execz .LBB0_1168
	v_readlane_b32 s34, v254, 43
	v_lshlrev_b64 v[100:101], 6, v[114:115]
	v_readlane_b32 s35, v254, 44
	v_lshl_add_u64 v[100:101], s[42:43], 0, v[100:101]
	s_mov_b32 s31, s35
	v_lshl_add_u64 v[100:101], s[52:53], 2, v[100:101]
	s_lshl_b32 s34, s64, 2
	v_writelane_b32 v254, s30, 43
	v_lshl_add_u64 v[100:101], v[100:101], 0, s[34:35]
	s_waitcnt lgkmcnt(0)
	v_add_f32_e32 v98, v98, v99
	v_writelane_b32 v254, s31, 44
	global_store_dword v[100:101], v98, off
.LBB0_1168:
	s_or_b64 exec, exec, s[54:55]
	v_or_b32_e32 v98, 32, v138
	s_waitcnt lgkmcnt(0)
	v_ashrrev_i32_e32 v99, 31, v98
	v_lshlrev_b64 v[100:101], 10, v[98:99]
	v_lshl_add_u64 v[104:105], v[100:101], 0, v[136:137]
	v_readlane_b32 s34, v255, 6
	v_lshlrev_b64 v[106:107], 2, v[104:105]
	v_readlane_b32 s35, v255, 7
	v_readlane_b32 s68, v254, 45
	v_readlane_b32 s74, v254, 51
	v_lshl_add_u64 v[108:109], s[34:35], 0, v[106:107]
	v_readlane_b32 s75, v254, 52
	v_lshl_add_u64 v[104:105], v[104:105], 1, s[6:7]
	v_readlane_b32 s69, v254, 46
	v_lshl_add_u64 v[106:107], s[74:75], 0, v[106:107]
	v_readlane_b32 s70, v254, 47
	v_readlane_b32 s71, v254, 48
	v_readlane_b32 s72, v254, 49
	v_readlane_b32 s73, v254, 50
	s_waitcnt vmcnt(17) lgkmcnt(0)
	v_pk_add_f32 v[96:97], v[96:97], v[166:167]
	v_pk_add_f32 v[94:95], v[94:95], v[164:165]
	v_cvt_pk_bf16_f32 v101, v96, v97
	v_cvt_pk_bf16_f32 v100, v94, v95
	global_store_dwordx4 v[106:107], v[94:97], off
	global_store_dwordx2 v[104:105], v[100:101], off
	v_mul_f32_e32 v95, v95, v95
	v_mul_f32_e32 v97, v97, v97
	v_fmac_f32_e32 v95, v94, v94
	v_fmac_f32_e32 v97, v96, v96
	v_add_f32_e32 v94, v95, v97
	s_waitcnt vmcnt(18) lgkmcnt(0)
	v_pk_add_f32 v[92:93], v[92:93], v[170:171]
	v_pk_add_f32 v[90:91], v[90:91], v[168:169]
	v_cvt_pk_bf16_f32 v101, v92, v93
	v_cvt_pk_bf16_f32 v100, v90, v91
	global_store_dwordx4 v[106:107], v[90:93], off offset:64
	global_store_dwordx2 v[104:105], v[100:101], off offset:32
	v_mul_f32_e32 v91, v91, v91
	v_mul_f32_e32 v93, v93, v93
	v_fmac_f32_e32 v91, v90, v90
	v_fmac_f32_e32 v93, v92, v92
	v_add_f32_e32 v90, v91, v93
	v_add_f32_e32 v90, v94, v90
	s_waitcnt vmcnt(19) lgkmcnt(0)
	v_pk_add_f32 v[88:89], v[88:89], v[174:175]
	v_pk_add_f32 v[86:87], v[86:87], v[172:173]
	v_cvt_pk_bf16_f32 v101, v88, v89
	v_cvt_pk_bf16_f32 v100, v86, v87
	global_store_dwordx4 v[106:107], v[86:89], off offset:512
	global_store_dwordx2 v[104:105], v[100:101], off offset:256
	v_mul_f32_e32 v87, v87, v87
	v_mul_f32_e32 v89, v89, v89
	v_fmac_f32_e32 v87, v86, v86
	v_fmac_f32_e32 v89, v88, v88
	v_add_f32_e32 v86, v87, v89
	v_add_f32_e32 v88, v90, v86
	s_waitcnt vmcnt(20) lgkmcnt(0)
	v_pk_add_f32 v[86:87], v[84:85], v[178:179]
	v_pk_add_f32 v[84:85], v[82:83], v[176:177]
	v_add_u32_e32 v231, 0x80000, v230
	global_load_dwordx4 v[164:167], v231, s[76:77]
	global_load_dwordx4 v[168:171], v231, s[76:77] offset:64
	global_load_dwordx4 v[172:175], v231, s[76:77] offset:512
	global_load_dwordx4 v[176:179], v231, s[76:77] offset:576
	v_mul_f32_e32 v83, v87, v87
	v_mul_f32_e32 v82, v85, v85
	v_fmac_f32_e32 v82, v84, v84
	v_fmac_f32_e32 v83, v86, v86
	v_add_f32_e32 v82, v82, v83
	v_add_f32_e32 v82, v88, v82
	ds_bpermute_b32 v83, v118, v82
	global_store_dwordx4 v[106:107], v[84:87], off offset:576
	s_waitcnt lgkmcnt(0)
	v_add_f32_e32 v82, v82, v83
	ds_bpermute_b32 v83, v116, v82
	v_cvt_pk_bf16_f32 v84, v84, v85
	v_cvt_pk_bf16_f32 v85, v86, v87
	global_store_dwordx2 v[104:105], v[84:85], off offset:288
	s_mov_b64 s[54:55], exec
	v_readlane_b32 s92, v252, 6
	s_and_b64 s[34:35], s[54:55], s[0:1]
	v_readlane_b32 s93, v252, 7
	v_mov_b32_e32 v200, v202
	s_mov_b64 exec, s[34:35]
	s_cbranch_execz .LBB0_1170
	v_readlane_b32 s34, v254, 43
	v_lshlrev_b64 v[84:85], 6, v[98:99]
	v_readlane_b32 s35, v254, 44
	v_lshl_add_u64 v[84:85], s[42:43], 0, v[84:85]
	s_mov_b32 s31, s35
	v_lshl_add_u64 v[84:85], s[52:53], 2, v[84:85]
	s_lshl_b32 s34, s64, 2
	v_writelane_b32 v254, s30, 43
	v_lshl_add_u64 v[84:85], v[84:85], 0, s[34:35]
	s_waitcnt lgkmcnt(0)
	v_add_f32_e32 v82, v82, v83
	v_writelane_b32 v254, s31, 44
	global_store_dword v[84:85], v82, off
.LBB0_1170:
	s_or_b64 exec, exec, s[54:55]
	v_or_b32_e32 v82, 48, v138
	s_waitcnt lgkmcnt(0)
	v_ashrrev_i32_e32 v83, 31, v82
	v_lshlrev_b64 v[84:85], 10, v[82:83]
	v_lshl_add_u64 v[88:89], v[84:85], 0, v[136:137]
	v_readlane_b32 s34, v255, 6
	v_lshlrev_b64 v[90:91], 2, v[88:89]
	v_readlane_b32 s35, v255, 7
	v_readlane_b32 s84, v254, 45
	v_readlane_b32 s90, v254, 51
	v_lshl_add_u64 v[92:93], s[34:35], 0, v[90:91]
	v_readlane_b32 s91, v254, 52
	v_lshl_add_u64 v[88:89], v[88:89], 1, s[6:7]
	v_readlane_b32 s85, v254, 46
	v_lshl_add_u64 v[90:91], s[90:91], 0, v[90:91]
	v_readlane_b32 s86, v254, 47
	v_readlane_b32 s87, v254, 48
	v_readlane_b32 s88, v254, 49
	v_readlane_b32 s89, v254, 50
	s_waitcnt vmcnt(17) lgkmcnt(0)
	v_pk_add_f32 v[80:81], v[80:81], v[182:183]
	v_pk_add_f32 v[78:79], v[78:79], v[180:181]
	v_cvt_pk_bf16_f32 v85, v80, v81
	v_cvt_pk_bf16_f32 v84, v78, v79
	global_store_dwordx4 v[90:91], v[78:81], off
	global_store_dwordx2 v[88:89], v[84:85], off
	v_mul_f32_e32 v79, v79, v79
	v_mul_f32_e32 v81, v81, v81
	v_fmac_f32_e32 v79, v78, v78
	v_fmac_f32_e32 v81, v80, v80
	v_add_f32_e32 v78, v79, v81
	s_waitcnt vmcnt(18) lgkmcnt(0)
	v_pk_add_f32 v[76:77], v[76:77], v[186:187]
	v_pk_add_f32 v[74:75], v[74:75], v[184:185]
	v_cvt_pk_bf16_f32 v85, v76, v77
	v_cvt_pk_bf16_f32 v84, v74, v75
	global_store_dwordx4 v[90:91], v[74:77], off offset:64
	global_store_dwordx2 v[88:89], v[84:85], off offset:32
	v_mul_f32_e32 v75, v75, v75
	v_mul_f32_e32 v77, v77, v77
	v_fmac_f32_e32 v75, v74, v74
	v_fmac_f32_e32 v77, v76, v76
	v_add_f32_e32 v74, v75, v77
	v_add_f32_e32 v74, v78, v74
	s_waitcnt vmcnt(19) lgkmcnt(0)
	v_pk_add_f32 v[72:73], v[72:73], v[190:191]
	v_pk_add_f32 v[70:71], v[70:71], v[188:189]
	v_cvt_pk_bf16_f32 v85, v72, v73
	v_cvt_pk_bf16_f32 v84, v70, v71
	global_store_dwordx4 v[90:91], v[70:73], off offset:512
	global_store_dwordx2 v[88:89], v[84:85], off offset:256
	v_mul_f32_e32 v71, v71, v71
	v_mul_f32_e32 v73, v73, v73
	v_fmac_f32_e32 v71, v70, v70
	v_fmac_f32_e32 v73, v72, v72
	v_add_f32_e32 v70, v71, v73
	v_add_f32_e32 v72, v74, v70
	s_waitcnt vmcnt(20) lgkmcnt(0)
	v_pk_add_f32 v[70:71], v[68:69], v[228:229]
	v_pk_add_f32 v[68:69], v[66:67], v[226:227]
	v_add_u32_e32 v231, 0x90000, v230
	global_load_dwordx4 v[180:183], v231, s[76:77]
	global_load_dwordx4 v[184:187], v231, s[76:77] offset:64
	global_load_dwordx4 v[188:191], v231, s[76:77] offset:512
	global_load_dwordx4 v[226:229], v231, s[76:77] offset:576
	v_mul_f32_e32 v67, v71, v71
	v_mul_f32_e32 v66, v69, v69
	v_fmac_f32_e32 v66, v68, v68
	v_fmac_f32_e32 v67, v70, v70
	v_add_f32_e32 v66, v66, v67
	v_add_f32_e32 v66, v72, v66
	ds_bpermute_b32 v67, v118, v66
	global_store_dwordx4 v[90:91], v[68:71], off offset:576
	s_waitcnt lgkmcnt(0)
	v_add_f32_e32 v66, v66, v67
	ds_bpermute_b32 v67, v116, v66
	v_cvt_pk_bf16_f32 v68, v68, v69
	v_cvt_pk_bf16_f32 v69, v70, v71
	global_store_dwordx2 v[88:89], v[68:69], off offset:288
	s_and_saveexec_b64 s[54:55], s[0:1]
	s_cbranch_execz .LBB0_1172
	v_readlane_b32 s34, v254, 43
	v_lshlrev_b64 v[68:69], 6, v[82:83]
	v_readlane_b32 s35, v254, 44
	v_lshl_add_u64 v[68:69], s[42:43], 0, v[68:69]
	s_mov_b32 s31, s35
	v_lshl_add_u64 v[68:69], s[52:53], 2, v[68:69]
	s_lshl_b32 s34, s64, 2
	v_writelane_b32 v254, s30, 43
	v_lshl_add_u64 v[68:69], v[68:69], 0, s[34:35]
	s_waitcnt lgkmcnt(0)
	v_add_f32_e32 v66, v66, v67
	v_writelane_b32 v254, s31, 44
	global_store_dword v[68:69], v66, off
.LBB0_1172:
	s_or_b64 exec, exec, s[54:55]
	v_add_u32_e32 v66, 0x80, v138
	s_waitcnt lgkmcnt(0)
	v_ashrrev_i32_e32 v67, 31, v66
	v_lshlrev_b64 v[68:69], 10, v[66:67]
	v_lshl_add_u64 v[72:73], v[68:69], 0, v[136:137]
	v_readlane_b32 s34, v255, 6
	v_lshlrev_b64 v[74:75], 2, v[72:73]
	v_readlane_b32 s35, v255, 7
	v_readlane_b32 s84, v254, 45
	v_readlane_b32 s90, v254, 51
	v_lshl_add_u64 v[76:77], s[34:35], 0, v[74:75]
	v_readlane_b32 s91, v254, 52
	v_lshl_add_u64 v[72:73], v[72:73], 1, s[6:7]
	v_readlane_b32 s85, v254, 46
	v_lshl_add_u64 v[74:75], s[90:91], 0, v[74:75]
	v_readlane_b32 s86, v254, 47
	v_readlane_b32 s87, v254, 48
	v_readlane_b32 s88, v254, 49
	v_readlane_b32 s89, v254, 50
	s_waitcnt vmcnt(17) lgkmcnt(0)
	v_pk_add_f32 v[62:63], v[62:63], v[166:167]
	v_pk_add_f32 v[60:61], v[60:61], v[164:165]
	v_cvt_pk_bf16_f32 v69, v62, v63
	v_cvt_pk_bf16_f32 v68, v60, v61
	global_store_dwordx4 v[74:75], v[60:63], off
	global_store_dwordx2 v[72:73], v[68:69], off
	v_mul_f32_e32 v61, v61, v61
	v_mul_f32_e32 v63, v63, v63
	v_fmac_f32_e32 v61, v60, v60
	v_fmac_f32_e32 v63, v62, v62
	v_add_f32_e32 v60, v61, v63
	s_waitcnt vmcnt(18) lgkmcnt(0)
	v_pk_add_f32 v[58:59], v[58:59], v[170:171]
	v_pk_add_f32 v[56:57], v[56:57], v[168:169]
	v_cvt_pk_bf16_f32 v69, v58, v59
	v_cvt_pk_bf16_f32 v68, v56, v57
	global_store_dwordx4 v[74:75], v[56:59], off offset:64
	global_store_dwordx2 v[72:73], v[68:69], off offset:32
	v_mul_f32_e32 v57, v57, v57
	v_mul_f32_e32 v59, v59, v59
	v_fmac_f32_e32 v57, v56, v56
	v_fmac_f32_e32 v59, v58, v58
	v_add_f32_e32 v56, v57, v59
	v_add_f32_e32 v56, v60, v56
	s_waitcnt vmcnt(19) lgkmcnt(0)
	v_pk_add_f32 v[54:55], v[54:55], v[174:175]
	v_pk_add_f32 v[52:53], v[52:53], v[172:173]
	v_cvt_pk_bf16_f32 v69, v54, v55
	v_cvt_pk_bf16_f32 v68, v52, v53
	global_store_dwordx4 v[74:75], v[52:55], off offset:512
	global_store_dwordx2 v[72:73], v[68:69], off offset:256
	v_mul_f32_e32 v53, v53, v53
	v_mul_f32_e32 v55, v55, v55
	v_fmac_f32_e32 v53, v52, v52
	v_fmac_f32_e32 v55, v54, v54
	v_add_f32_e32 v52, v53, v55
	v_add_f32_e32 v54, v56, v52
	s_waitcnt vmcnt(20) lgkmcnt(0)
	v_pk_add_f32 v[52:53], v[50:51], v[178:179]
	v_pk_add_f32 v[50:51], v[48:49], v[176:177]
	v_add_u32_e32 v231, 0xa0000, v230
	global_load_dwordx4 v[164:167], v231, s[76:77]
	global_load_dwordx4 v[168:171], v231, s[76:77] offset:64
	global_load_dwordx4 v[172:175], v231, s[76:77] offset:512
	global_load_dwordx4 v[176:179], v231, s[76:77] offset:576
	v_mul_f32_e32 v49, v53, v53
	v_mul_f32_e32 v48, v51, v51
	v_fmac_f32_e32 v48, v50, v50
	v_fmac_f32_e32 v49, v52, v52
	v_add_f32_e32 v48, v48, v49
	v_add_f32_e32 v48, v54, v48
	ds_bpermute_b32 v49, v118, v48
	global_store_dwordx4 v[74:75], v[50:53], off offset:576
	s_waitcnt lgkmcnt(0)
	v_add_f32_e32 v48, v48, v49
	ds_bpermute_b32 v49, v116, v48
	v_cvt_pk_bf16_f32 v50, v50, v51
	v_cvt_pk_bf16_f32 v51, v52, v53
	global_store_dwordx2 v[72:73], v[50:51], off offset:288
	s_and_saveexec_b64 s[54:55], s[0:1]
	s_cbranch_execz .LBB0_1174
	v_readlane_b32 s34, v254, 43
	v_lshlrev_b64 v[50:51], 6, v[66:67]
	v_readlane_b32 s35, v254, 44
	v_lshl_add_u64 v[50:51], s[42:43], 0, v[50:51]
	s_mov_b32 s31, s35
	v_lshl_add_u64 v[50:51], s[52:53], 2, v[50:51]
	s_lshl_b32 s34, s64, 2
	v_writelane_b32 v254, s30, 43
	v_lshl_add_u64 v[50:51], v[50:51], 0, s[34:35]
	s_waitcnt lgkmcnt(0)
	v_add_f32_e32 v48, v48, v49
	v_writelane_b32 v254, s31, 44
	global_store_dword v[50:51], v48, off
.LBB0_1174:
	s_or_b64 exec, exec, s[54:55]
	v_add_u32_e32 v48, 0x90, v138
	s_waitcnt lgkmcnt(0)
	v_ashrrev_i32_e32 v49, 31, v48
	v_lshlrev_b64 v[50:51], 10, v[48:49]
	v_lshl_add_u64 v[54:55], v[50:51], 0, v[136:137]
	v_readlane_b32 s34, v255, 6
	v_lshlrev_b64 v[56:57], 2, v[54:55]
	v_readlane_b32 s35, v255, 7
	v_readlane_b32 s84, v254, 45
	v_readlane_b32 s90, v254, 51
	v_lshl_add_u64 v[58:59], s[34:35], 0, v[56:57]
	v_readlane_b32 s91, v254, 52
	v_lshl_add_u64 v[54:55], v[54:55], 1, s[6:7]
	v_readlane_b32 s85, v254, 46
	v_lshl_add_u64 v[56:57], s[90:91], 0, v[56:57]
	v_readlane_b32 s86, v254, 47
	v_readlane_b32 s87, v254, 48
	v_readlane_b32 s88, v254, 49
	v_readlane_b32 s89, v254, 50
	s_waitcnt vmcnt(17) lgkmcnt(0)
	v_pk_add_f32 v[46:47], v[46:47], v[182:183]
	v_pk_add_f32 v[44:45], v[44:45], v[180:181]
	v_cvt_pk_bf16_f32 v51, v46, v47
	v_cvt_pk_bf16_f32 v50, v44, v45
	global_store_dwordx4 v[56:57], v[44:47], off
	global_store_dwordx2 v[54:55], v[50:51], off
	v_mul_f32_e32 v45, v45, v45
	v_mul_f32_e32 v47, v47, v47
	v_fmac_f32_e32 v45, v44, v44
	v_fmac_f32_e32 v47, v46, v46
	v_add_f32_e32 v44, v45, v47
	s_waitcnt vmcnt(18) lgkmcnt(0)
	v_pk_add_f32 v[42:43], v[42:43], v[186:187]
	v_pk_add_f32 v[40:41], v[40:41], v[184:185]
	v_cvt_pk_bf16_f32 v51, v42, v43
	v_cvt_pk_bf16_f32 v50, v40, v41
	global_store_dwordx4 v[56:57], v[40:43], off offset:64
	global_store_dwordx2 v[54:55], v[50:51], off offset:32
	v_mul_f32_e32 v41, v41, v41
	v_mul_f32_e32 v43, v43, v43
	v_fmac_f32_e32 v41, v40, v40
	v_fmac_f32_e32 v43, v42, v42
	v_add_f32_e32 v40, v41, v43
	v_add_f32_e32 v40, v44, v40
	s_waitcnt vmcnt(19) lgkmcnt(0)
	v_pk_add_f32 v[38:39], v[38:39], v[190:191]
	v_pk_add_f32 v[36:37], v[36:37], v[188:189]
	v_cvt_pk_bf16_f32 v51, v38, v39
	v_cvt_pk_bf16_f32 v50, v36, v37
	global_store_dwordx4 v[56:57], v[36:39], off offset:512
	global_store_dwordx2 v[54:55], v[50:51], off offset:256
	v_mul_f32_e32 v37, v37, v37
	v_mul_f32_e32 v39, v39, v39
	v_fmac_f32_e32 v37, v36, v36
	v_fmac_f32_e32 v39, v38, v38
	v_add_f32_e32 v36, v37, v39
	v_add_f32_e32 v38, v40, v36
	s_waitcnt vmcnt(20) lgkmcnt(0)
	v_pk_add_f32 v[36:37], v[34:35], v[228:229]
	v_pk_add_f32 v[34:35], v[32:33], v[226:227]
	v_add_u32_e32 v231, 0xb0000, v230
	global_load_dwordx4 v[180:183], v231, s[76:77]
	global_load_dwordx4 v[184:187], v231, s[76:77] offset:64
	global_load_dwordx4 v[188:191], v231, s[76:77] offset:512
	global_load_dwordx4 v[226:229], v231, s[76:77] offset:576
	v_mul_f32_e32 v33, v37, v37
	v_mul_f32_e32 v32, v35, v35
	v_fmac_f32_e32 v32, v34, v34
	v_fmac_f32_e32 v33, v36, v36
	v_add_f32_e32 v32, v32, v33
	v_add_f32_e32 v32, v38, v32
	ds_bpermute_b32 v33, v118, v32
	global_store_dwordx4 v[56:57], v[34:37], off offset:576
	s_waitcnt lgkmcnt(0)
	v_add_f32_e32 v32, v32, v33
	ds_bpermute_b32 v33, v116, v32
	v_cvt_pk_bf16_f32 v34, v34, v35
	v_cvt_pk_bf16_f32 v35, v36, v37
	global_store_dwordx2 v[54:55], v[34:35], off offset:288
	s_and_saveexec_b64 s[54:55], s[0:1]
	s_cbranch_execz .LBB0_1176
	v_readlane_b32 s34, v254, 43
	v_lshlrev_b64 v[34:35], 6, v[48:49]
	v_readlane_b32 s35, v254, 44
	v_lshl_add_u64 v[34:35], s[42:43], 0, v[34:35]
	s_mov_b32 s31, s35
	v_lshl_add_u64 v[34:35], s[52:53], 2, v[34:35]
	s_lshl_b32 s34, s64, 2
	v_writelane_b32 v254, s30, 43
	v_lshl_add_u64 v[34:35], v[34:35], 0, s[34:35]
	s_waitcnt lgkmcnt(0)
	v_add_f32_e32 v32, v32, v33
	v_writelane_b32 v254, s31, 44
	global_store_dword v[34:35], v32, off
.LBB0_1176:
	s_or_b64 exec, exec, s[54:55]
	v_add_u32_e32 v32, 0xa0, v138
	s_waitcnt lgkmcnt(0)
	v_ashrrev_i32_e32 v33, 31, v32
	v_lshlrev_b64 v[34:35], 10, v[32:33]
	v_lshl_add_u64 v[38:39], v[34:35], 0, v[136:137]
	v_readlane_b32 s34, v255, 6
	v_lshlrev_b64 v[40:41], 2, v[38:39]
	v_readlane_b32 s35, v255, 7
	v_readlane_b32 s84, v254, 45
	v_readlane_b32 s90, v254, 51
	v_lshl_add_u64 v[42:43], s[34:35], 0, v[40:41]
	v_readlane_b32 s91, v254, 52
	v_lshl_add_u64 v[38:39], v[38:39], 1, s[6:7]
	v_readlane_b32 s85, v254, 46
	v_lshl_add_u64 v[40:41], s[90:91], 0, v[40:41]
	v_readlane_b32 s86, v254, 47
	v_readlane_b32 s87, v254, 48
	v_readlane_b32 s88, v254, 49
	v_readlane_b32 s89, v254, 50
	s_waitcnt vmcnt(17) lgkmcnt(0)
	v_pk_add_f32 v[30:31], v[30:31], v[166:167]
	v_pk_add_f32 v[28:29], v[28:29], v[164:165]
	v_cvt_pk_bf16_f32 v35, v30, v31
	v_cvt_pk_bf16_f32 v34, v28, v29
	global_store_dwordx4 v[40:41], v[28:31], off
	global_store_dwordx2 v[38:39], v[34:35], off
	v_mul_f32_e32 v29, v29, v29
	v_mul_f32_e32 v31, v31, v31
	v_fmac_f32_e32 v29, v28, v28
	v_fmac_f32_e32 v31, v30, v30
	v_add_f32_e32 v28, v29, v31
	s_waitcnt vmcnt(18) lgkmcnt(0)
	v_pk_add_f32 v[26:27], v[26:27], v[170:171]
	v_pk_add_f32 v[24:25], v[24:25], v[168:169]
	v_cvt_pk_bf16_f32 v35, v26, v27
	v_cvt_pk_bf16_f32 v34, v24, v25
	global_store_dwordx4 v[40:41], v[24:27], off offset:64
	global_store_dwordx2 v[38:39], v[34:35], off offset:32
	v_mul_f32_e32 v25, v25, v25
	v_mul_f32_e32 v27, v27, v27
	v_fmac_f32_e32 v25, v24, v24
	v_fmac_f32_e32 v27, v26, v26
	v_add_f32_e32 v24, v25, v27
	v_add_f32_e32 v24, v28, v24
	s_waitcnt vmcnt(19) lgkmcnt(0)
	v_pk_add_f32 v[22:23], v[22:23], v[174:175]
	v_pk_add_f32 v[20:21], v[20:21], v[172:173]
	v_cvt_pk_bf16_f32 v35, v22, v23
	v_cvt_pk_bf16_f32 v34, v20, v21
	global_store_dwordx4 v[40:41], v[20:23], off offset:512
	global_store_dwordx2 v[38:39], v[34:35], off offset:256
	v_mul_f32_e32 v21, v21, v21
	v_mul_f32_e32 v23, v23, v23
	v_fmac_f32_e32 v21, v20, v20
	v_fmac_f32_e32 v23, v22, v22
	v_add_f32_e32 v20, v21, v23
	v_add_f32_e32 v22, v24, v20
	s_waitcnt vmcnt(20) lgkmcnt(0)
	v_pk_add_f32 v[20:21], v[18:19], v[178:179]
	v_pk_add_f32 v[18:19], v[16:17], v[176:177]
	v_mul_f32_e32 v17, v21, v21
	v_mul_f32_e32 v16, v19, v19
	v_fmac_f32_e32 v16, v18, v18
	v_fmac_f32_e32 v17, v20, v20
	v_add_f32_e32 v16, v16, v17
	v_add_f32_e32 v16, v22, v16
	ds_bpermute_b32 v17, v118, v16
	global_store_dwordx4 v[40:41], v[18:21], off offset:576
	s_waitcnt lgkmcnt(0)
	v_add_f32_e32 v16, v16, v17
	ds_bpermute_b32 v17, v116, v16
	v_cvt_pk_bf16_f32 v18, v18, v19
	v_cvt_pk_bf16_f32 v19, v20, v21
	global_store_dwordx2 v[38:39], v[18:19], off offset:288
	s_and_saveexec_b64 s[54:55], s[0:1]
	s_cbranch_execz .LBB0_1178
	v_readlane_b32 s34, v254, 43
	v_lshlrev_b64 v[18:19], 6, v[32:33]
	v_readlane_b32 s35, v254, 44
	v_lshl_add_u64 v[18:19], s[42:43], 0, v[18:19]
	s_mov_b32 s31, s35
	v_lshl_add_u64 v[18:19], s[52:53], 2, v[18:19]
	s_lshl_b32 s34, s64, 2
	v_writelane_b32 v254, s30, 43
	v_lshl_add_u64 v[18:19], v[18:19], 0, s[34:35]
	s_waitcnt lgkmcnt(0)
	v_add_f32_e32 v16, v16, v17
	v_writelane_b32 v254, s31, 44
	global_store_dword v[18:19], v16, off
.LBB0_1178:
	s_or_b64 exec, exec, s[54:55]
	v_add_u32_e32 v16, 0xb0, v138
	s_waitcnt lgkmcnt(0)
	v_ashrrev_i32_e32 v17, 31, v16
	v_lshlrev_b64 v[18:19], 10, v[16:17]
	v_lshl_add_u64 v[22:23], v[18:19], 0, v[136:137]
	v_readlane_b32 s34, v255, 6
	v_lshlrev_b64 v[24:25], 2, v[22:23]
	v_readlane_b32 s35, v255, 7
	v_readlane_b32 s84, v254, 45
	v_readlane_b32 s90, v254, 51
	v_lshl_add_u64 v[26:27], s[34:35], 0, v[24:25]
	v_readlane_b32 s91, v254, 52
	v_lshl_add_u64 v[22:23], v[22:23], 1, s[6:7]
	v_readlane_b32 s85, v254, 46
	v_lshl_add_u64 v[24:25], s[90:91], 0, v[24:25]
	v_readlane_b32 s86, v254, 47
	v_readlane_b32 s87, v254, 48
	v_readlane_b32 s88, v254, 49
	v_readlane_b32 s89, v254, 50
	s_waitcnt vmcnt(13) lgkmcnt(0)
	v_pk_add_f32 v[14:15], v[14:15], v[182:183]
	v_pk_add_f32 v[12:13], v[12:13], v[180:181]
	v_cvt_pk_bf16_f32 v19, v14, v15
	v_cvt_pk_bf16_f32 v18, v12, v13
	global_store_dwordx4 v[24:25], v[12:15], off
	global_store_dwordx2 v[22:23], v[18:19], off
	v_mul_f32_e32 v13, v13, v13
	v_mul_f32_e32 v15, v15, v15
	v_fmac_f32_e32 v13, v12, v12
	v_fmac_f32_e32 v15, v14, v14
	v_add_f32_e32 v12, v13, v15
	s_waitcnt vmcnt(14) lgkmcnt(0)
	v_pk_add_f32 v[10:11], v[10:11], v[186:187]
	v_pk_add_f32 v[8:9], v[8:9], v[184:185]
	v_cvt_pk_bf16_f32 v19, v10, v11
	v_cvt_pk_bf16_f32 v18, v8, v9
	global_store_dwordx4 v[24:25], v[8:11], off offset:64
	global_store_dwordx2 v[22:23], v[18:19], off offset:32
	v_mul_f32_e32 v9, v9, v9
	v_mul_f32_e32 v11, v11, v11
	v_fmac_f32_e32 v9, v8, v8
	v_fmac_f32_e32 v11, v10, v10
	v_add_f32_e32 v8, v9, v11
	v_add_f32_e32 v8, v12, v8
	s_waitcnt vmcnt(15) lgkmcnt(0)
	v_pk_add_f32 v[6:7], v[6:7], v[190:191]
	v_pk_add_f32 v[4:5], v[4:5], v[188:189]
	v_cvt_pk_bf16_f32 v19, v6, v7
	v_cvt_pk_bf16_f32 v18, v4, v5
	global_store_dwordx4 v[24:25], v[4:7], off offset:512
	global_store_dwordx2 v[22:23], v[18:19], off offset:256
	v_mul_f32_e32 v5, v5, v5
	v_mul_f32_e32 v7, v7, v7
	v_fmac_f32_e32 v5, v4, v4
	v_fmac_f32_e32 v7, v6, v6
	v_add_f32_e32 v4, v5, v7
	v_add_f32_e32 v6, v8, v4
	s_waitcnt vmcnt(16) lgkmcnt(0)
	v_pk_add_f32 v[4:5], v[2:3], v[228:229]
	v_pk_add_f32 v[2:3], v[0:1], v[226:227]
	v_mul_f32_e32 v1, v5, v5
	v_mul_f32_e32 v0, v3, v3
	v_fmac_f32_e32 v0, v2, v2
	v_fmac_f32_e32 v1, v4, v4
	v_add_f32_e32 v0, v0, v1
	v_add_f32_e32 v0, v6, v0
	ds_bpermute_b32 v1, v118, v0
	global_store_dwordx4 v[24:25], v[2:5], off offset:576
	s_waitcnt lgkmcnt(0)
	v_add_f32_e32 v0, v0, v1
	ds_bpermute_b32 v1, v116, v0
	v_cvt_pk_bf16_f32 v2, v2, v3
	v_cvt_pk_bf16_f32 v3, v4, v5
	global_store_dwordx2 v[22:23], v[2:3], off offset:288
	s_and_saveexec_b64 s[54:55], s[0:1]
	s_cbranch_execz .LBB0_1180
	v_readlane_b32 s34, v254, 43
	v_lshlrev_b64 v[2:3], 6, v[16:17]
	v_readlane_b32 s35, v254, 44
	v_lshl_add_u64 v[2:3], s[42:43], 0, v[2:3]
	s_mov_b32 s31, s35
	v_lshl_add_u64 v[2:3], s[52:53], 2, v[2:3]
	s_lshl_b32 s34, s64, 2
	v_writelane_b32 v254, s30, 43
	v_lshl_add_u64 v[2:3], v[2:3], 0, s[34:35]
	s_waitcnt lgkmcnt(0)
	v_add_f32_e32 v0, v0, v1
	v_writelane_b32 v254, s31, 44
	global_store_dword v[2:3], v0, off

.LBB0_1685:
	v_lshl_add_u32 v138, s27, 8, v144
	v_lshl_or_b32 v136, s26, 8, v146
	v_readlane_b32 s76, v254, 51
	v_readlane_b32 s77, v254, 52
	v_lshl_add_u32 v230, v138, 10, v136
	v_lshlrev_b32_e32 v230, 2, v230
	s_nop 3
	global_load_dwordx4 v[164:167], v230, s[76:77]
	global_load_dwordx4 v[168:171], v230, s[76:77] offset:64
	global_load_dwordx4 v[172:175], v230, s[76:77] offset:512
	global_load_dwordx4 v[176:179], v230, s[76:77] offset:576
	v_add_u32_e32 v231, 0x10000, v230
	global_load_dwordx4 v[180:183], v231, s[76:77]
	global_load_dwordx4 v[184:187], v231, s[76:77] offset:64
	global_load_dwordx4 v[188:191], v231, s[76:77] offset:512
	global_load_dwordx4 v[226:229], v231, s[76:77] offset:576
	v_ashrrev_i32_e32 v139, 31, v138
	v_ashrrev_i32_e32 v137, 31, v136
	v_lshlrev_b64 v[140:141], 10, v[138:139]
	v_readlane_b32 s84, v254, 45
	v_lshl_add_u64 v[142:143], v[140:141], 0, v[136:137]
	v_readlane_b32 s90, v254, 51
	v_readlane_b32 s91, v254, 52
	s_lshl_b32 s50, s26, 2
	v_cndmask_b32_e64 v152, 0, 1, s[44:45]
	v_lshl_add_u64 v[140:141], v[142:143], 2, s[90:91]
	s_ashr_i32 s51, s50, 31
	v_cmp_ne_u32_e64 s[38:39], 1, v152
	s_andn2_b64 vcc, exec, s[44:45]
	v_readlane_b32 s33, v255, 5
	v_readlane_b32 s85, v254, 46
	v_readlane_b32 s86, v254, 47
	v_readlane_b32 s87, v254, 48
	v_readlane_b32 s88, v254, 49
	v_readlane_b32 s89, v254, 50
	s_waitcnt vmcnt(7)
	v_pk_add_f32 v[128:129], v[128:129], v[166:167]
	v_pk_add_f32 v[126:127], v[126:127], v[164:165]
	global_store_dwordx4 v[140:141], v[126:129], off
	s_cbranch_vccnz .LBB0_1728
	v_cvt_pk_bf16_f32 v148, v126, v127
	v_mul_f32_e32 v127, v127, v127
	v_cvt_pk_bf16_f32 v149, v128, v129
	v_lshl_add_u64 v[142:143], v[142:143], 1, s[4:5]
	v_fmac_f32_e32 v127, v126, v126
	v_mul_f32_e32 v126, v129, v129
	global_store_dwordx2 v[142:143], v[148:149], off
	v_fmac_f32_e32 v126, v128, v128
	v_add_f32_e32 v150, v127, v126
	s_waitcnt vmcnt(8)
	v_pk_add_f32 v[128:129], v[124:125], v[170:171]
	v_pk_add_f32 v[126:127], v[122:123], v[168:169]
	global_store_dwordx4 v[140:141], v[126:129], off offset:64
	v_cvt_pk_bf16_f32 v148, v126, v127
	v_cvt_pk_bf16_f32 v149, v128, v129
	v_mul_f32_e32 v127, v127, v127
	v_fmac_f32_e32 v127, v126, v126
	v_mul_f32_e32 v126, v129, v129
	v_fmac_f32_e32 v126, v128, v128
	global_store_dwordx2 v[142:143], v[148:149], off offset:32
	v_add_f32_e32 v126, v127, v126
	v_add_f32_e32 v150, v150, v126
	s_waitcnt vmcnt(9)
	v_pk_add_f32 v[128:129], v[120:121], v[174:175]
	v_pk_add_f32 v[126:127], v[118:119], v[172:173]
	global_store_dwordx4 v[140:141], v[126:129], off offset:512
	v_cvt_pk_bf16_f32 v148, v126, v127
	v_cvt_pk_bf16_f32 v149, v128, v129
	v_mul_f32_e32 v127, v127, v127
	v_fmac_f32_e32 v127, v126, v126
	v_mul_f32_e32 v126, v129, v129
	v_fmac_f32_e32 v126, v128, v128
	global_store_dwordx2 v[142:143], v[148:149], off offset:256
	v_add_f32_e32 v126, v127, v126
	v_add_f32_e32 v150, v150, v126
	s_waitcnt vmcnt(10)
	v_pk_add_f32 v[128:129], v[116:117], v[178:179]
	v_pk_add_f32 v[126:127], v[114:115], v[176:177]
	v_add_u32_e32 v231, 0x20000, v230
	global_load_dwordx4 v[164:167], v231, s[76:77]
	global_load_dwordx4 v[168:171], v231, s[76:77] offset:64
	global_load_dwordx4 v[172:175], v231, s[76:77] offset:512
	global_load_dwordx4 v[176:179], v231, s[76:77] offset:576
	global_store_dwordx4 v[140:141], v[126:129], off offset:576
	v_cvt_pk_bf16_f32 v148, v126, v127
	v_cvt_pk_bf16_f32 v149, v128, v129
	v_mul_f32_e32 v127, v127, v127
	v_fmac_f32_e32 v127, v126, v126
	v_mul_f32_e32 v126, v129, v129
	v_fmac_f32_e32 v126, v128, v128
	v_and_b32_e32 v128, 64, v197
	v_add_f32_e32 v126, v127, v126
	v_xor_b32_e32 v127, 16, v197
	v_add_u32_e32 v128, 64, v128
	v_cmp_lt_i32_e32 vcc, v127, v128
	v_add_f32_e32 v126, v150, v126
	global_store_dwordx2 v[142:143], v[148:149], off offset:288
	v_cndmask_b32_e32 v127, v197, v127, vcc
	v_lshlrev_b32_e32 v127, 2, v127
	ds_bpermute_b32 v127, v127, v126
	s_waitcnt lgkmcnt(0)
	v_add_f32_e32 v126, v126, v127
	v_xor_b32_e32 v127, 32, v197
	v_cmp_lt_i32_e32 vcc, v127, v128
	s_nop 1
	v_cndmask_b32_e32 v127, v197, v127, vcc
	v_lshlrev_b32_e32 v127, 2, v127
	ds_bpermute_b32 v127, v127, v126
	s_and_saveexec_b64 s[52:53], s[0:1]
	s_cbranch_execz .LBB0_1688
	v_lshlrev_b64 v[128:129], 6, v[138:139]
	v_readlane_b32 s26, v254, 43
	v_lshl_add_u64 v[128:129], s[30:31], 0, v[128:129]
	v_readlane_b32 s27, v254, 44
	v_lshl_add_u64 v[128:129], s[50:51], 2, v[128:129]
	s_mov_b32 s29, s27
	s_lshl_b32 s28, s65, 2
	v_writelane_b32 v254, s26, 43
	v_lshl_add_u64 v[128:129], v[128:129], 0, s[28:29]
	s_waitcnt lgkmcnt(0)
	v_add_f32_e32 v126, v126, v127
	v_writelane_b32 v254, s27, 44
	global_store_dword v[128:129], v126, off

.LBB0_1689:
	s_waitcnt lgkmcnt(0)
	s_waitcnt vmcnt(7)
	v_pk_add_f32 v[124:125], v[124:125], v[170:171]
	v_pk_add_f32 v[122:123], v[122:123], v[168:169]
	global_store_dwordx4 v[140:141], v[122:125], off offset:64
	s_waitcnt vmcnt(7)
	v_pk_add_f32 v[120:121], v[120:121], v[174:175]
	v_pk_add_f32 v[118:119], v[118:119], v[172:173]
	global_store_dwordx4 v[140:141], v[118:121], off offset:512
	s_waitcnt vmcnt(7)
	v_pk_add_f32 v[116:117], v[116:117], v[178:179]
	v_pk_add_f32 v[114:115], v[114:115], v[176:177]
	v_add_u32_e32 v231, 0x20000, v230
	global_load_dwordx4 v[164:167], v231, s[76:77]
	global_load_dwordx4 v[168:171], v231, s[76:77] offset:64
	global_load_dwordx4 v[172:175], v231, s[76:77] offset:512
	global_load_dwordx4 v[176:179], v231, s[76:77] offset:576
	global_store_dwordx4 v[140:141], v[114:117], off offset:576
.LBB0_1690:
	s_nop 1
	v_or_b32_e32 v116, 16, v138
	v_ashrrev_i32_e32 v117, 31, v116
	v_lshlrev_b64 v[114:115], 10, v[116:117]
	v_readlane_b32 s84, v254, 45
	v_lshl_add_u64 v[118:119], v[114:115], 0, v[136:137]
	v_readlane_b32 s90, v254, 51
	v_readlane_b32 s91, v254, 52
	s_and_b64 vcc, exec, s[38:39]
	v_readlane_b32 s85, v254, 46
	v_lshl_add_u64 v[114:115], v[118:119], 2, s[90:91]
	v_readlane_b32 s86, v254, 47
	v_readlane_b32 s87, v254, 48
	v_readlane_b32 s88, v254, 49
	v_readlane_b32 s89, v254, 50
	s_waitcnt vmcnt(11)
	v_pk_add_f32 v[112:113], v[112:113], v[182:183]
	v_pk_add_f32 v[110:111], v[110:111], v[180:181]
	global_store_dwordx4 v[114:115], v[110:113], off
	s_cbranch_vccnz .LBB0_1729
	v_cvt_pk_bf16_f32 v120, v110, v111
	v_mul_f32_e32 v111, v111, v111
	v_cvt_pk_bf16_f32 v121, v112, v113
	v_lshl_add_u64 v[118:119], v[118:119], 1, s[4:5]
	v_fmac_f32_e32 v111, v110, v110
	v_mul_f32_e32 v110, v113, v113
	global_store_dwordx2 v[118:119], v[120:121], off
	v_fmac_f32_e32 v110, v112, v112
	v_add_f32_e32 v122, v111, v110
	s_waitcnt vmcnt(16)
	v_pk_add_f32 v[112:113], v[108:109], v[186:187]
	v_pk_add_f32 v[110:111], v[106:107], v[184:185]
	global_store_dwordx4 v[114:115], v[110:113], off offset:64
	v_cvt_pk_bf16_f32 v120, v110, v111
	v_cvt_pk_bf16_f32 v121, v112, v113
	v_mul_f32_e32 v111, v111, v111
	v_fmac_f32_e32 v111, v110, v110
	v_mul_f32_e32 v110, v113, v113
	v_fmac_f32_e32 v110, v112, v112
	global_store_dwordx2 v[118:119], v[120:121], off offset:32
	v_add_f32_e32 v110, v111, v110
	v_add_f32_e32 v122, v122, v110
	s_waitcnt vmcnt(17)
	v_pk_add_f32 v[112:113], v[104:105], v[190:191]
	v_pk_add_f32 v[110:111], v[102:103], v[188:189]
	global_store_dwordx4 v[114:115], v[110:113], off offset:512
	v_cvt_pk_bf16_f32 v120, v110, v111
	v_cvt_pk_bf16_f32 v121, v112, v113
	v_mul_f32_e32 v111, v111, v111
	v_fmac_f32_e32 v111, v110, v110
	v_mul_f32_e32 v110, v113, v113
	v_fmac_f32_e32 v110, v112, v112
	global_store_dwordx2 v[118:119], v[120:121], off offset:256
	v_add_f32_e32 v110, v111, v110
	v_add_f32_e32 v122, v122, v110
	s_waitcnt vmcnt(18)
	v_pk_add_f32 v[112:113], v[100:101], v[228:229]
	v_pk_add_f32 v[110:111], v[98:99], v[226:227]
	v_add_u32_e32 v231, 0x30000, v230
	global_load_dwordx4 v[180:183], v231, s[76:77]
	global_load_dwordx4 v[184:187], v231, s[76:77] offset:64
	global_load_dwordx4 v[188:191], v231, s[76:77] offset:512
	global_load_dwordx4 v[226:229], v231, s[76:77] offset:576
	global_store_dwordx4 v[114:115], v[110:113], off offset:576
	v_cvt_pk_bf16_f32 v120, v110, v111
	v_cvt_pk_bf16_f32 v121, v112, v113
	v_mul_f32_e32 v111, v111, v111
	v_fmac_f32_e32 v111, v110, v110
	v_mul_f32_e32 v110, v113, v113
	v_fmac_f32_e32 v110, v112, v112
	v_and_b32_e32 v112, 64, v197
	v_add_f32_e32 v110, v111, v110
	v_xor_b32_e32 v111, 16, v197
	v_add_u32_e32 v112, 64, v112
	v_cmp_lt_i32_e32 vcc, v111, v112
	v_add_f32_e32 v110, v122, v110
	global_store_dwordx2 v[118:119], v[120:121], off offset:288
	v_cndmask_b32_e32 v111, v197, v111, vcc
	v_lshlrev_b32_e32 v111, 2, v111
	ds_bpermute_b32 v111, v111, v110
	s_waitcnt lgkmcnt(0)
	v_add_f32_e32 v110, v110, v111
	v_xor_b32_e32 v111, 32, v197
	v_cmp_lt_i32_e32 vcc, v111, v112
	s_nop 1
	v_cndmask_b32_e32 v111, v197, v111, vcc
	v_lshlrev_b32_e32 v111, 2, v111
	ds_bpermute_b32 v111, v111, v110
	s_and_saveexec_b64 s[52:53], s[0:1]
	s_cbranch_execz .LBB0_1693
	v_lshlrev_b64 v[112:113], 6, v[116:117]
	v_readlane_b32 s26, v254, 43
	v_lshl_add_u64 v[112:113], s[30:31], 0, v[112:113]
	v_readlane_b32 s27, v254, 44
	v_lshl_add_u64 v[112:113], s[50:51], 2, v[112:113]
	s_mov_b32 s29, s27
	s_lshl_b32 s28, s65, 2
	v_writelane_b32 v254, s26, 43
	v_lshl_add_u64 v[112:113], v[112:113], 0, s[28:29]
	s_waitcnt lgkmcnt(0)
	v_add_f32_e32 v110, v110, v111
	v_writelane_b32 v254, s27, 44
	global_store_dword v[112:113], v110, off

.LBB0_1694:
	s_waitcnt lgkmcnt(0)
	s_waitcnt vmcnt(11)
	v_pk_add_f32 v[108:109], v[108:109], v[186:187]
	v_pk_add_f32 v[106:107], v[106:107], v[184:185]
	global_store_dwordx4 v[114:115], v[106:109], off offset:64
	s_waitcnt vmcnt(11)
	v_pk_add_f32 v[104:105], v[104:105], v[190:191]
	v_pk_add_f32 v[102:103], v[102:103], v[188:189]
	global_store_dwordx4 v[114:115], v[102:105], off offset:512
	s_waitcnt vmcnt(11)
	v_pk_add_f32 v[100:101], v[100:101], v[228:229]
	v_pk_add_f32 v[98:99], v[98:99], v[226:227]
	v_add_u32_e32 v231, 0x30000, v230
	global_load_dwordx4 v[180:183], v231, s[76:77]
	global_load_dwordx4 v[184:187], v231, s[76:77] offset:64
	global_load_dwordx4 v[188:191], v231, s[76:77] offset:512
	global_load_dwordx4 v[226:229], v231, s[76:77] offset:576
	global_store_dwordx4 v[114:115], v[98:101], off offset:576
.LBB0_1695:
	s_nop 1
	v_or_b32_e32 v100, 32, v138
	v_ashrrev_i32_e32 v101, 31, v100
	v_lshlrev_b64 v[98:99], 10, v[100:101]
	v_readlane_b32 s84, v254, 45
	v_lshl_add_u64 v[102:103], v[98:99], 0, v[136:137]
	v_readlane_b32 s90, v254, 51
	v_readlane_b32 s91, v254, 52
	s_and_b64 vcc, exec, s[38:39]
	v_readlane_b32 s85, v254, 46
	v_lshl_add_u64 v[98:99], v[102:103], 2, s[90:91]
	v_readlane_b32 s86, v254, 47
	v_readlane_b32 s87, v254, 48
	v_readlane_b32 s88, v254, 49
	v_readlane_b32 s89, v254, 50
	s_waitcnt vmcnt(12)
	v_pk_add_f32 v[96:97], v[96:97], v[166:167]
	v_pk_add_f32 v[94:95], v[94:95], v[164:165]
	global_store_dwordx4 v[98:99], v[94:97], off
	s_cbranch_vccnz .LBB0_1730
	v_cvt_pk_bf16_f32 v104, v94, v95
	v_mul_f32_e32 v95, v95, v95
	v_cvt_pk_bf16_f32 v105, v96, v97
	v_lshl_add_u64 v[102:103], v[102:103], 1, s[4:5]
	v_fmac_f32_e32 v95, v94, v94
	v_mul_f32_e32 v94, v97, v97
	global_store_dwordx2 v[102:103], v[104:105], off
	v_fmac_f32_e32 v94, v96, v96
	v_add_f32_e32 v106, v95, v94
	s_waitcnt vmcnt(18)
	v_pk_add_f32 v[96:97], v[92:93], v[170:171]
	v_pk_add_f32 v[94:95], v[90:91], v[168:169]
	global_store_dwordx4 v[98:99], v[94:97], off offset:64
	v_cvt_pk_bf16_f32 v104, v94, v95
	v_cvt_pk_bf16_f32 v105, v96, v97
	v_mul_f32_e32 v95, v95, v95
	v_fmac_f32_e32 v95, v94, v94
	v_mul_f32_e32 v94, v97, v97
	v_fmac_f32_e32 v94, v96, v96
	global_store_dwordx2 v[102:103], v[104:105], off offset:32
	v_add_f32_e32 v94, v95, v94
	v_add_f32_e32 v106, v106, v94
	s_waitcnt vmcnt(19)
	v_pk_add_f32 v[96:97], v[88:89], v[174:175]
	v_pk_add_f32 v[94:95], v[86:87], v[172:173]
	global_store_dwordx4 v[98:99], v[94:97], off offset:512
	v_cvt_pk_bf16_f32 v104, v94, v95
	v_cvt_pk_bf16_f32 v105, v96, v97
	v_mul_f32_e32 v95, v95, v95
	v_fmac_f32_e32 v95, v94, v94
	v_mul_f32_e32 v94, v97, v97
	v_fmac_f32_e32 v94, v96, v96
	global_store_dwordx2 v[102:103], v[104:105], off offset:256
	v_add_f32_e32 v94, v95, v94
	v_add_f32_e32 v106, v106, v94
	s_waitcnt vmcnt(20)
	v_pk_add_f32 v[96:97], v[84:85], v[178:179]
	v_pk_add_f32 v[94:95], v[82:83], v[176:177]
	v_add_u32_e32 v231, 0x80000, v230
	global_load_dwordx4 v[164:167], v231, s[76:77]
	global_load_dwordx4 v[168:171], v231, s[76:77] offset:64
	global_load_dwordx4 v[172:175], v231, s[76:77] offset:512
	global_load_dwordx4 v[176:179], v231, s[76:77] offset:576
	global_store_dwordx4 v[98:99], v[94:97], off offset:576
	v_cvt_pk_bf16_f32 v104, v94, v95
	v_cvt_pk_bf16_f32 v105, v96, v97
	v_mul_f32_e32 v95, v95, v95
	v_fmac_f32_e32 v95, v94, v94
	v_mul_f32_e32 v94, v97, v97
	v_fmac_f32_e32 v94, v96, v96
	v_and_b32_e32 v96, 64, v197
	v_add_f32_e32 v94, v95, v94
	v_xor_b32_e32 v95, 16, v197
	v_add_u32_e32 v96, 64, v96
	v_cmp_lt_i32_e32 vcc, v95, v96
	v_add_f32_e32 v94, v106, v94
	global_store_dwordx2 v[102:103], v[104:105], off offset:288
	v_cndmask_b32_e32 v95, v197, v95, vcc
	v_lshlrev_b32_e32 v95, 2, v95
	ds_bpermute_b32 v95, v95, v94
	s_waitcnt lgkmcnt(0)
	v_add_f32_e32 v94, v94, v95
	v_xor_b32_e32 v95, 32, v197
	v_cmp_lt_i32_e32 vcc, v95, v96
	s_nop 1
	v_cndmask_b32_e32 v95, v197, v95, vcc
	v_lshlrev_b32_e32 v95, 2, v95
	ds_bpermute_b32 v95, v95, v94
	s_and_saveexec_b64 s[52:53], s[0:1]
	s_cbranch_execz .LBB0_1698
	v_lshlrev_b64 v[96:97], 6, v[100:101]
	v_readlane_b32 s26, v254, 43
	v_lshl_add_u64 v[96:97], s[30:31], 0, v[96:97]
	v_readlane_b32 s27, v254, 44
	v_lshl_add_u64 v[96:97], s[50:51], 2, v[96:97]
	s_mov_b32 s29, s27
	s_lshl_b32 s28, s65, 2
	v_writelane_b32 v254, s26, 43
	v_lshl_add_u64 v[96:97], v[96:97], 0, s[28:29]
	s_waitcnt lgkmcnt(0)
	v_add_f32_e32 v94, v94, v95
	v_writelane_b32 v254, s27, 44
	global_store_dword v[96:97], v94, off

.LBB0_1699:
	s_waitcnt lgkmcnt(0)
	s_waitcnt vmcnt(12)
	v_pk_add_f32 v[92:93], v[92:93], v[170:171]
	v_pk_add_f32 v[90:91], v[90:91], v[168:169]
	global_store_dwordx4 v[98:99], v[90:93], off offset:64
	s_waitcnt vmcnt(12)
	v_pk_add_f32 v[88:89], v[88:89], v[174:175]
	v_pk_add_f32 v[86:87], v[86:87], v[172:173]
	global_store_dwordx4 v[98:99], v[86:89], off offset:512
	s_waitcnt vmcnt(12)
	v_pk_add_f32 v[84:85], v[84:85], v[178:179]
	v_pk_add_f32 v[82:83], v[82:83], v[176:177]
	v_add_u32_e32 v231, 0x80000, v230
	global_load_dwordx4 v[164:167], v231, s[76:77]
	global_load_dwordx4 v[168:171], v231, s[76:77] offset:64
	global_load_dwordx4 v[172:175], v231, s[76:77] offset:512
	global_load_dwordx4 v[176:179], v231, s[76:77] offset:576
	global_store_dwordx4 v[98:99], v[82:85], off offset:576
.LBB0_1700:
	s_nop 1
	v_or_b32_e32 v84, 48, v138
	v_ashrrev_i32_e32 v85, 31, v84
	v_lshlrev_b64 v[82:83], 10, v[84:85]
	v_readlane_b32 s84, v254, 45
	v_lshl_add_u64 v[86:87], v[82:83], 0, v[136:137]
	v_readlane_b32 s90, v254, 51
	v_readlane_b32 s91, v254, 52
	s_and_b64 vcc, exec, s[38:39]
	v_readlane_b32 s85, v254, 46
	v_lshl_add_u64 v[82:83], v[86:87], 2, s[90:91]
	v_readlane_b32 s86, v254, 47
	v_readlane_b32 s87, v254, 48
	v_readlane_b32 s88, v254, 49
	v_readlane_b32 s89, v254, 50
	s_waitcnt vmcnt(12)
	v_pk_add_f32 v[80:81], v[80:81], v[182:183]
	v_pk_add_f32 v[78:79], v[78:79], v[180:181]
	global_store_dwordx4 v[82:83], v[78:81], off
	s_cbranch_vccnz .LBB0_1731
	v_cvt_pk_bf16_f32 v88, v78, v79
	v_mul_f32_e32 v79, v79, v79
	v_cvt_pk_bf16_f32 v89, v80, v81
	v_lshl_add_u64 v[86:87], v[86:87], 1, s[4:5]
	v_fmac_f32_e32 v79, v78, v78
	v_mul_f32_e32 v78, v81, v81
	global_store_dwordx2 v[86:87], v[88:89], off
	v_fmac_f32_e32 v78, v80, v80
	v_add_f32_e32 v90, v79, v78
	s_waitcnt vmcnt(18)
	v_pk_add_f32 v[80:81], v[76:77], v[186:187]
	v_pk_add_f32 v[78:79], v[74:75], v[184:185]
	global_store_dwordx4 v[82:83], v[78:81], off offset:64
	v_cvt_pk_bf16_f32 v88, v78, v79
	v_cvt_pk_bf16_f32 v89, v80, v81
	v_mul_f32_e32 v79, v79, v79
	v_fmac_f32_e32 v79, v78, v78
	v_mul_f32_e32 v78, v81, v81
	v_fmac_f32_e32 v78, v80, v80
	global_store_dwordx2 v[86:87], v[88:89], off offset:32
	v_add_f32_e32 v78, v79, v78
	v_add_f32_e32 v90, v90, v78
	s_waitcnt vmcnt(19)
	v_pk_add_f32 v[80:81], v[72:73], v[190:191]
	v_pk_add_f32 v[78:79], v[70:71], v[188:189]
	global_store_dwordx4 v[82:83], v[78:81], off offset:512
	v_cvt_pk_bf16_f32 v88, v78, v79
	v_cvt_pk_bf16_f32 v89, v80, v81
	v_mul_f32_e32 v79, v79, v79
	v_fmac_f32_e32 v79, v78, v78
	v_mul_f32_e32 v78, v81, v81
	v_fmac_f32_e32 v78, v80, v80
	global_store_dwordx2 v[86:87], v[88:89], off offset:256
	v_add_f32_e32 v78, v79, v78
	v_add_f32_e32 v90, v90, v78
	s_waitcnt vmcnt(20)
	v_pk_add_f32 v[80:81], v[68:69], v[228:229]
	v_pk_add_f32 v[78:79], v[66:67], v[226:227]
	v_add_u32_e32 v231, 0x90000, v230
	global_load_dwordx4 v[180:183], v231, s[76:77]
	global_load_dwordx4 v[184:187], v231, s[76:77] offset:64
	global_load_dwordx4 v[188:191], v231, s[76:77] offset:512
	global_load_dwordx4 v[226:229], v231, s[76:77] offset:576
	global_store_dwordx4 v[82:83], v[78:81], off offset:576
	v_cvt_pk_bf16_f32 v88, v78, v79
	v_cvt_pk_bf16_f32 v89, v80, v81
	v_mul_f32_e32 v79, v79, v79
	v_fmac_f32_e32 v79, v78, v78
	v_mul_f32_e32 v78, v81, v81
	v_fmac_f32_e32 v78, v80, v80
	v_and_b32_e32 v80, 64, v197
	v_add_f32_e32 v78, v79, v78
	v_xor_b32_e32 v79, 16, v197
	v_add_u32_e32 v80, 64, v80
	v_cmp_lt_i32_e32 vcc, v79, v80
	v_add_f32_e32 v78, v90, v78
	global_store_dwordx2 v[86:87], v[88:89], off offset:288
	v_cndmask_b32_e32 v79, v197, v79, vcc
	v_lshlrev_b32_e32 v79, 2, v79
	ds_bpermute_b32 v79, v79, v78
	s_waitcnt lgkmcnt(0)
	v_add_f32_e32 v78, v78, v79
	v_xor_b32_e32 v79, 32, v197
	v_cmp_lt_i32_e32 vcc, v79, v80
	s_nop 1
	v_cndmask_b32_e32 v79, v197, v79, vcc
	v_lshlrev_b32_e32 v79, 2, v79
	ds_bpermute_b32 v79, v79, v78
	s_and_saveexec_b64 s[52:53], s[0:1]
	s_cbranch_execz .LBB0_1703
	v_lshlrev_b64 v[80:81], 6, v[84:85]
	v_readlane_b32 s26, v254, 43
	v_lshl_add_u64 v[80:81], s[30:31], 0, v[80:81]
	v_readlane_b32 s27, v254, 44
	v_lshl_add_u64 v[80:81], s[50:51], 2, v[80:81]
	s_mov_b32 s29, s27
	s_lshl_b32 s28, s65, 2
	v_writelane_b32 v254, s26, 43
	v_lshl_add_u64 v[80:81], v[80:81], 0, s[28:29]
	s_waitcnt lgkmcnt(0)
	v_add_f32_e32 v78, v78, v79
	v_writelane_b32 v254, s27, 44
	global_store_dword v[80:81], v78, off

.LBB0_1704:
	s_waitcnt lgkmcnt(0)
	s_waitcnt vmcnt(12)
	v_pk_add_f32 v[76:77], v[76:77], v[186:187]
	v_pk_add_f32 v[74:75], v[74:75], v[184:185]
	global_store_dwordx4 v[82:83], v[74:77], off offset:64
	s_waitcnt vmcnt(12)
	v_pk_add_f32 v[72:73], v[72:73], v[190:191]
	v_pk_add_f32 v[70:71], v[70:71], v[188:189]
	global_store_dwordx4 v[82:83], v[70:73], off offset:512
	s_waitcnt vmcnt(12)
	v_pk_add_f32 v[68:69], v[68:69], v[228:229]
	v_pk_add_f32 v[66:67], v[66:67], v[226:227]
	v_add_u32_e32 v231, 0x90000, v230
	global_load_dwordx4 v[180:183], v231, s[76:77]
	global_load_dwordx4 v[184:187], v231, s[76:77] offset:64
	global_load_dwordx4 v[188:191], v231, s[76:77] offset:512
	global_load_dwordx4 v[226:229], v231, s[76:77] offset:576
	global_store_dwordx4 v[82:83], v[66:69], off offset:576
.LBB0_1705:
	s_nop 1
	v_add_u32_e32 v68, 0x80, v138
	v_ashrrev_i32_e32 v69, 31, v68
	v_lshlrev_b64 v[66:67], 10, v[68:69]
	v_readlane_b32 s84, v254, 45
	v_lshl_add_u64 v[70:71], v[66:67], 0, v[136:137]
	v_readlane_b32 s90, v254, 51
	v_readlane_b32 s91, v254, 52
	s_and_b64 vcc, exec, s[38:39]
	v_readlane_b32 s85, v254, 46
	v_lshl_add_u64 v[66:67], v[70:71], 2, s[90:91]
	v_readlane_b32 s86, v254, 47
	v_readlane_b32 s87, v254, 48
	v_readlane_b32 s88, v254, 49
	v_readlane_b32 s89, v254, 50
	s_waitcnt vmcnt(12)
	v_pk_add_f32 v[62:63], v[62:63], v[166:167]
	v_pk_add_f32 v[60:61], v[60:61], v[164:165]
	global_store_dwordx4 v[66:67], v[60:63], off
	s_cbranch_vccnz .LBB0_1732
	v_cvt_pk_bf16_f32 v72, v60, v61
	v_mul_f32_e32 v61, v61, v61
	v_cvt_pk_bf16_f32 v73, v62, v63
	v_lshl_add_u64 v[70:71], v[70:71], 1, s[4:5]
	v_fmac_f32_e32 v61, v60, v60
	v_mul_f32_e32 v60, v63, v63
	global_store_dwordx2 v[70:71], v[72:73], off
	v_fmac_f32_e32 v60, v62, v62
	v_add_f32_e32 v74, v61, v60
	s_waitcnt vmcnt(18)
	v_pk_add_f32 v[62:63], v[58:59], v[170:171]
	v_pk_add_f32 v[60:61], v[56:57], v[168:169]
	global_store_dwordx4 v[66:67], v[60:63], off offset:64
	v_cvt_pk_bf16_f32 v72, v60, v61
	v_cvt_pk_bf16_f32 v73, v62, v63
	v_mul_f32_e32 v61, v61, v61
	v_fmac_f32_e32 v61, v60, v60
	v_mul_f32_e32 v60, v63, v63
	v_fmac_f32_e32 v60, v62, v62
	global_store_dwordx2 v[70:71], v[72:73], off offset:32
	v_add_f32_e32 v60, v61, v60
	v_add_f32_e32 v74, v74, v60
	s_waitcnt vmcnt(19)
	v_pk_add_f32 v[62:63], v[54:55], v[174:175]
	v_pk_add_f32 v[60:61], v[52:53], v[172:173]
	global_store_dwordx4 v[66:67], v[60:63], off offset:512
	v_cvt_pk_bf16_f32 v72, v60, v61
	v_cvt_pk_bf16_f32 v73, v62, v63
	v_mul_f32_e32 v61, v61, v61
	v_fmac_f32_e32 v61, v60, v60
	v_mul_f32_e32 v60, v63, v63
	v_fmac_f32_e32 v60, v62, v62
	global_store_dwordx2 v[70:71], v[72:73], off offset:256
	v_add_f32_e32 v60, v61, v60
	v_add_f32_e32 v74, v74, v60
	s_waitcnt vmcnt(20)
	v_pk_add_f32 v[62:63], v[50:51], v[178:179]
	v_pk_add_f32 v[60:61], v[48:49], v[176:177]
	v_add_u32_e32 v231, 0xa0000, v230
	global_load_dwordx4 v[164:167], v231, s[76:77]
	global_load_dwordx4 v[168:171], v231, s[76:77] offset:64
	global_load_dwordx4 v[172:175], v231, s[76:77] offset:512
	global_load_dwordx4 v[176:179], v231, s[76:77] offset:576
	global_store_dwordx4 v[66:67], v[60:63], off offset:576
	v_cvt_pk_bf16_f32 v72, v60, v61
	v_cvt_pk_bf16_f32 v73, v62, v63
	v_mul_f32_e32 v61, v61, v61
	v_fmac_f32_e32 v61, v60, v60
	v_mul_f32_e32 v60, v63, v63
	v_fmac_f32_e32 v60, v62, v62
	v_and_b32_e32 v62, 64, v197
	v_add_f32_e32 v60, v61, v60
	v_xor_b32_e32 v61, 16, v197
	v_add_u32_e32 v62, 64, v62
	v_cmp_lt_i32_e32 vcc, v61, v62
	v_add_f32_e32 v60, v74, v60
	global_store_dwordx2 v[70:71], v[72:73], off offset:288
	v_cndmask_b32_e32 v61, v197, v61, vcc
	v_lshlrev_b32_e32 v61, 2, v61
	ds_bpermute_b32 v61, v61, v60
	s_waitcnt lgkmcnt(0)
	v_add_f32_e32 v60, v60, v61
	v_xor_b32_e32 v61, 32, v197
	v_cmp_lt_i32_e32 vcc, v61, v62
	s_nop 1
	v_cndmask_b32_e32 v61, v197, v61, vcc
	v_lshlrev_b32_e32 v61, 2, v61
	ds_bpermute_b32 v61, v61, v60
	s_and_saveexec_b64 s[52:53], s[0:1]
	s_cbranch_execz .LBB0_1708
	v_lshlrev_b64 v[62:63], 6, v[68:69]
	v_readlane_b32 s26, v254, 43
	v_lshl_add_u64 v[62:63], s[30:31], 0, v[62:63]
	v_readlane_b32 s27, v254, 44
	v_lshl_add_u64 v[62:63], s[50:51], 2, v[62:63]
	s_mov_b32 s29, s27
	s_lshl_b32 s28, s65, 2
	v_writelane_b32 v254, s26, 43
	v_lshl_add_u64 v[62:63], v[62:63], 0, s[28:29]
	s_waitcnt lgkmcnt(0)
	v_add_f32_e32 v60, v60, v61
	v_writelane_b32 v254, s27, 44
	global_store_dword v[62:63], v60, off

.LBB0_1709:
	s_waitcnt lgkmcnt(0)
	s_waitcnt vmcnt(12)
	v_pk_add_f32 v[58:59], v[58:59], v[170:171]
	v_pk_add_f32 v[56:57], v[56:57], v[168:169]
	global_store_dwordx4 v[66:67], v[56:59], off offset:64
	s_waitcnt vmcnt(12)
	v_pk_add_f32 v[54:55], v[54:55], v[174:175]
	v_pk_add_f32 v[52:53], v[52:53], v[172:173]
	global_store_dwordx4 v[66:67], v[52:55], off offset:512
	s_waitcnt vmcnt(12)
	v_pk_add_f32 v[50:51], v[50:51], v[178:179]
	v_pk_add_f32 v[48:49], v[48:49], v[176:177]
	v_add_u32_e32 v231, 0xa0000, v230
	global_load_dwordx4 v[164:167], v231, s[76:77]
	global_load_dwordx4 v[168:171], v231, s[76:77] offset:64
	global_load_dwordx4 v[172:175], v231, s[76:77] offset:512
	global_load_dwordx4 v[176:179], v231, s[76:77] offset:576
	global_store_dwordx4 v[66:67], v[48:51], off offset:576
.LBB0_1710:
	s_nop 1
	v_add_u32_e32 v50, 0x90, v138
	v_ashrrev_i32_e32 v51, 31, v50
	v_lshlrev_b64 v[48:49], 10, v[50:51]
	v_readlane_b32 s84, v254, 45
	v_lshl_add_u64 v[52:53], v[48:49], 0, v[136:137]
	v_readlane_b32 s90, v254, 51
	v_readlane_b32 s91, v254, 52
	s_and_b64 vcc, exec, s[38:39]
	v_readlane_b32 s85, v254, 46
	v_lshl_add_u64 v[48:49], v[52:53], 2, s[90:91]
	v_readlane_b32 s86, v254, 47
	v_readlane_b32 s87, v254, 48
	v_readlane_b32 s88, v254, 49
	v_readlane_b32 s89, v254, 50
	s_waitcnt vmcnt(12)
	v_pk_add_f32 v[46:47], v[46:47], v[182:183]
	v_pk_add_f32 v[44:45], v[44:45], v[180:181]
	global_store_dwordx4 v[48:49], v[44:47], off
	s_cbranch_vccnz .LBB0_1733
	v_cvt_pk_bf16_f32 v54, v44, v45
	v_mul_f32_e32 v45, v45, v45
	v_cvt_pk_bf16_f32 v55, v46, v47
	v_lshl_add_u64 v[52:53], v[52:53], 1, s[4:5]
	v_fmac_f32_e32 v45, v44, v44
	v_mul_f32_e32 v44, v47, v47
	global_store_dwordx2 v[52:53], v[54:55], off
	v_fmac_f32_e32 v44, v46, v46
	v_add_f32_e32 v56, v45, v44
	s_waitcnt vmcnt(18)
	v_pk_add_f32 v[46:47], v[42:43], v[186:187]
	v_pk_add_f32 v[44:45], v[40:41], v[184:185]
	global_store_dwordx4 v[48:49], v[44:47], off offset:64
	v_cvt_pk_bf16_f32 v54, v44, v45
	v_cvt_pk_bf16_f32 v55, v46, v47
	v_mul_f32_e32 v45, v45, v45
	v_fmac_f32_e32 v45, v44, v44
	v_mul_f32_e32 v44, v47, v47
	v_fmac_f32_e32 v44, v46, v46
	global_store_dwordx2 v[52:53], v[54:55], off offset:32
	v_add_f32_e32 v44, v45, v44
	v_add_f32_e32 v56, v56, v44
	s_waitcnt vmcnt(19)
	v_pk_add_f32 v[46:47], v[38:39], v[190:191]
	v_pk_add_f32 v[44:45], v[36:37], v[188:189]
	global_store_dwordx4 v[48:49], v[44:47], off offset:512
	v_cvt_pk_bf16_f32 v54, v44, v45
	v_cvt_pk_bf16_f32 v55, v46, v47
	v_mul_f32_e32 v45, v45, v45
	v_fmac_f32_e32 v45, v44, v44
	v_mul_f32_e32 v44, v47, v47
	v_fmac_f32_e32 v44, v46, v46
	global_store_dwordx2 v[52:53], v[54:55], off offset:256
	v_add_f32_e32 v44, v45, v44
	v_add_f32_e32 v56, v56, v44
	s_waitcnt vmcnt(20)
	v_pk_add_f32 v[46:47], v[34:35], v[228:229]
	v_pk_add_f32 v[44:45], v[32:33], v[226:227]
	v_add_u32_e32 v231, 0xb0000, v230
	global_load_dwordx4 v[180:183], v231, s[76:77]
	global_load_dwordx4 v[184:187], v231, s[76:77] offset:64
	global_load_dwordx4 v[188:191], v231, s[76:77] offset:512
	global_load_dwordx4 v[226:229], v231, s[76:77] offset:576
	global_store_dwordx4 v[48:49], v[44:47], off offset:576
	v_cvt_pk_bf16_f32 v54, v44, v45
	v_cvt_pk_bf16_f32 v55, v46, v47
	v_mul_f32_e32 v45, v45, v45
	v_fmac_f32_e32 v45, v44, v44
	v_mul_f32_e32 v44, v47, v47
	v_fmac_f32_e32 v44, v46, v46
	v_and_b32_e32 v46, 64, v197
	v_add_f32_e32 v44, v45, v44
	v_xor_b32_e32 v45, 16, v197
	v_add_u32_e32 v46, 64, v46
	v_cmp_lt_i32_e32 vcc, v45, v46
	v_add_f32_e32 v44, v56, v44
	global_store_dwordx2 v[52:53], v[54:55], off offset:288
	v_cndmask_b32_e32 v45, v197, v45, vcc
	v_lshlrev_b32_e32 v45, 2, v45
	ds_bpermute_b32 v45, v45, v44
	s_waitcnt lgkmcnt(0)
	v_add_f32_e32 v44, v44, v45
	v_xor_b32_e32 v45, 32, v197
	v_cmp_lt_i32_e32 vcc, v45, v46
	s_nop 1
	v_cndmask_b32_e32 v45, v197, v45, vcc
	v_lshlrev_b32_e32 v45, 2, v45
	ds_bpermute_b32 v45, v45, v44
	s_and_saveexec_b64 s[52:53], s[0:1]
	s_cbranch_execz .LBB0_1713
	v_lshlrev_b64 v[46:47], 6, v[50:51]
	v_readlane_b32 s26, v254, 43
	v_lshl_add_u64 v[46:47], s[30:31], 0, v[46:47]
	v_readlane_b32 s27, v254, 44
	v_lshl_add_u64 v[46:47], s[50:51], 2, v[46:47]
	s_mov_b32 s29, s27
	s_lshl_b32 s28, s65, 2
	v_writelane_b32 v254, s26, 43
	v_lshl_add_u64 v[46:47], v[46:47], 0, s[28:29]
	s_waitcnt lgkmcnt(0)
	v_add_f32_e32 v44, v44, v45
	v_writelane_b32 v254, s27, 44
	global_store_dword v[46:47], v44, off

.LBB0_1714:
	s_waitcnt lgkmcnt(0)
	s_waitcnt vmcnt(12)
	v_pk_add_f32 v[42:43], v[42:43], v[186:187]
	v_pk_add_f32 v[40:41], v[40:41], v[184:185]
	global_store_dwordx4 v[48:49], v[40:43], off offset:64
	s_waitcnt vmcnt(12)
	v_pk_add_f32 v[38:39], v[38:39], v[190:191]
	v_pk_add_f32 v[36:37], v[36:37], v[188:189]
	global_store_dwordx4 v[48:49], v[36:39], off offset:512
	s_waitcnt vmcnt(12)
	v_pk_add_f32 v[34:35], v[34:35], v[228:229]
	v_pk_add_f32 v[32:33], v[32:33], v[226:227]
	v_add_u32_e32 v231, 0xb0000, v230
	global_load_dwordx4 v[180:183], v231, s[76:77]
	global_load_dwordx4 v[184:187], v231, s[76:77] offset:64
	global_load_dwordx4 v[188:191], v231, s[76:77] offset:512
	global_load_dwordx4 v[226:229], v231, s[76:77] offset:576
	global_store_dwordx4 v[48:49], v[32:35], off offset:576
.LBB0_1715:
	s_nop 1
	v_add_u32_e32 v34, 0xa0, v138
	v_ashrrev_i32_e32 v35, 31, v34
	v_lshlrev_b64 v[32:33], 10, v[34:35]
	v_readlane_b32 s84, v254, 45
	v_lshl_add_u64 v[36:37], v[32:33], 0, v[136:137]
	v_readlane_b32 s90, v254, 51
	v_readlane_b32 s91, v254, 52
	s_and_b64 vcc, exec, s[38:39]
	v_readlane_b32 s85, v254, 46
	v_lshl_add_u64 v[32:33], v[36:37], 2, s[90:91]
	v_readlane_b32 s86, v254, 47
	v_readlane_b32 s87, v254, 48
	v_readlane_b32 s88, v254, 49
	v_readlane_b32 s89, v254, 50
	s_waitcnt vmcnt(12)
	v_pk_add_f32 v[30:31], v[30:31], v[166:167]
	v_pk_add_f32 v[28:29], v[28:29], v[164:165]
	global_store_dwordx4 v[32:33], v[28:31], off
	s_cbranch_vccnz .LBB0_1734
	v_cvt_pk_bf16_f32 v38, v28, v29
	v_mul_f32_e32 v29, v29, v29
	v_cvt_pk_bf16_f32 v39, v30, v31
	v_lshl_add_u64 v[36:37], v[36:37], 1, s[4:5]
	v_fmac_f32_e32 v29, v28, v28
	v_mul_f32_e32 v28, v31, v31
	global_store_dwordx2 v[36:37], v[38:39], off
	v_fmac_f32_e32 v28, v30, v30
	v_add_f32_e32 v40, v29, v28
	s_waitcnt vmcnt(18)
	v_pk_add_f32 v[30:31], v[26:27], v[170:171]
	v_pk_add_f32 v[28:29], v[24:25], v[168:169]
	global_store_dwordx4 v[32:33], v[28:31], off offset:64
	v_cvt_pk_bf16_f32 v38, v28, v29
	v_cvt_pk_bf16_f32 v39, v30, v31
	v_mul_f32_e32 v29, v29, v29
	v_fmac_f32_e32 v29, v28, v28
	v_mul_f32_e32 v28, v31, v31
	v_fmac_f32_e32 v28, v30, v30
	global_store_dwordx2 v[36:37], v[38:39], off offset:32
	v_add_f32_e32 v28, v29, v28
	v_add_f32_e32 v40, v40, v28
	s_waitcnt vmcnt(19)
	v_pk_add_f32 v[30:31], v[22:23], v[174:175]
	v_pk_add_f32 v[28:29], v[20:21], v[172:173]
	global_store_dwordx4 v[32:33], v[28:31], off offset:512
	v_cvt_pk_bf16_f32 v38, v28, v29
	v_cvt_pk_bf16_f32 v39, v30, v31
	v_mul_f32_e32 v29, v29, v29
	v_fmac_f32_e32 v29, v28, v28
	v_mul_f32_e32 v28, v31, v31
	v_fmac_f32_e32 v28, v30, v30
	global_store_dwordx2 v[36:37], v[38:39], off offset:256
	v_add_f32_e32 v28, v29, v28
	v_add_f32_e32 v40, v40, v28
	s_waitcnt vmcnt(20)
	v_pk_add_f32 v[30:31], v[18:19], v[178:179]
	v_pk_add_f32 v[28:29], v[16:17], v[176:177]
	global_store_dwordx4 v[32:33], v[28:31], off offset:576
	v_cvt_pk_bf16_f32 v38, v28, v29
	v_cvt_pk_bf16_f32 v39, v30, v31
	v_mul_f32_e32 v29, v29, v29
	v_fmac_f32_e32 v29, v28, v28
	v_mul_f32_e32 v28, v31, v31
	v_fmac_f32_e32 v28, v30, v30
	v_and_b32_e32 v30, 64, v197
	v_add_f32_e32 v28, v29, v28
	v_xor_b32_e32 v29, 16, v197
	v_add_u32_e32 v30, 64, v30
	v_cmp_lt_i32_e32 vcc, v29, v30
	v_add_f32_e32 v28, v40, v28
	global_store_dwordx2 v[36:37], v[38:39], off offset:288
	v_cndmask_b32_e32 v29, v197, v29, vcc
	v_lshlrev_b32_e32 v29, 2, v29
	ds_bpermute_b32 v29, v29, v28
	s_waitcnt lgkmcnt(0)
	v_add_f32_e32 v28, v28, v29
	v_xor_b32_e32 v29, 32, v197
	v_cmp_lt_i32_e32 vcc, v29, v30
	s_nop 1
	v_cndmask_b32_e32 v29, v197, v29, vcc
	v_lshlrev_b32_e32 v29, 2, v29
	ds_bpermute_b32 v29, v29, v28
	s_and_saveexec_b64 s[52:53], s[0:1]
	s_cbranch_execz .LBB0_1718
	v_lshlrev_b64 v[30:31], 6, v[34:35]
	v_readlane_b32 s26, v254, 43
	v_lshl_add_u64 v[30:31], s[30:31], 0, v[30:31]
	v_readlane_b32 s27, v254, 44
	v_lshl_add_u64 v[30:31], s[50:51], 2, v[30:31]
	s_mov_b32 s29, s27
	s_lshl_b32 s28, s65, 2
	v_writelane_b32 v254, s26, 43
	v_lshl_add_u64 v[30:31], v[30:31], 0, s[28:29]
	s_waitcnt lgkmcnt(0)
	v_add_f32_e32 v28, v28, v29
	v_writelane_b32 v254, s27, 44
	global_store_dword v[30:31], v28, off

.LBB0_1719:
	s_waitcnt lgkmcnt(0)
	s_waitcnt vmcnt(12)
	v_pk_add_f32 v[26:27], v[26:27], v[170:171]
	v_pk_add_f32 v[24:25], v[24:25], v[168:169]
	global_store_dwordx4 v[32:33], v[24:27], off offset:64
	s_waitcnt vmcnt(12)
	v_pk_add_f32 v[22:23], v[22:23], v[174:175]
	v_pk_add_f32 v[20:21], v[20:21], v[172:173]
	global_store_dwordx4 v[32:33], v[20:23], off offset:512
	s_waitcnt vmcnt(12)
	v_pk_add_f32 v[18:19], v[18:19], v[178:179]
	v_pk_add_f32 v[16:17], v[16:17], v[176:177]
	global_store_dwordx4 v[32:33], v[16:19], off offset:576
.LBB0_1720:
	s_nop 1
	v_add_u32_e32 v18, 0xb0, v138
	v_ashrrev_i32_e32 v19, 31, v18
	v_lshlrev_b64 v[16:17], 10, v[18:19]
	v_readlane_b32 s84, v254, 45
	v_lshl_add_u64 v[20:21], v[16:17], 0, v[136:137]
	v_readlane_b32 s90, v254, 51
	v_readlane_b32 s91, v254, 52
	s_and_b64 vcc, exec, s[38:39]
	v_readlane_b32 s85, v254, 46
	v_lshl_add_u64 v[16:17], v[20:21], 2, s[90:91]
	v_readlane_b32 s86, v254, 47
	v_readlane_b32 s87, v254, 48
	v_readlane_b32 s88, v254, 49
	v_readlane_b32 s89, v254, 50
	s_waitcnt vmcnt(8)
	v_pk_add_f32 v[14:15], v[14:15], v[182:183]
	v_pk_add_f32 v[12:13], v[12:13], v[180:181]
	global_store_dwordx4 v[16:17], v[12:15], off
	s_cbranch_vccnz .LBB0_1735
	v_cvt_pk_bf16_f32 v22, v12, v13
	v_mul_f32_e32 v13, v13, v13
	v_cvt_pk_bf16_f32 v23, v14, v15
	v_lshl_add_u64 v[20:21], v[20:21], 1, s[4:5]
	v_fmac_f32_e32 v13, v12, v12
	v_mul_f32_e32 v12, v15, v15
	global_store_dwordx2 v[20:21], v[22:23], off
	v_fmac_f32_e32 v12, v14, v14
	v_add_f32_e32 v24, v13, v12
	s_waitcnt vmcnt(14)
	v_pk_add_f32 v[14:15], v[10:11], v[186:187]
	v_pk_add_f32 v[12:13], v[8:9], v[184:185]
	global_store_dwordx4 v[16:17], v[12:15], off offset:64
	v_cvt_pk_bf16_f32 v22, v12, v13
	v_cvt_pk_bf16_f32 v23, v14, v15
	v_mul_f32_e32 v13, v13, v13
	v_fmac_f32_e32 v13, v12, v12
	v_mul_f32_e32 v12, v15, v15
	v_fmac_f32_e32 v12, v14, v14
	global_store_dwordx2 v[20:21], v[22:23], off offset:32
	v_add_f32_e32 v12, v13, v12
	v_add_f32_e32 v24, v24, v12
	s_waitcnt vmcnt(15)
	v_pk_add_f32 v[14:15], v[6:7], v[190:191]
	v_pk_add_f32 v[12:13], v[4:5], v[188:189]
	global_store_dwordx4 v[16:17], v[12:15], off offset:512
	v_cvt_pk_bf16_f32 v22, v12, v13
	v_cvt_pk_bf16_f32 v23, v14, v15
	v_mul_f32_e32 v13, v13, v13
	v_fmac_f32_e32 v13, v12, v12
	v_mul_f32_e32 v12, v15, v15
	v_fmac_f32_e32 v12, v14, v14
	global_store_dwordx2 v[20:21], v[22:23], off offset:256
	v_add_f32_e32 v12, v13, v12
	v_add_f32_e32 v24, v24, v12
	s_waitcnt vmcnt(16)
	v_pk_add_f32 v[14:15], v[2:3], v[228:229]
	v_pk_add_f32 v[12:13], v[0:1], v[226:227]
	global_store_dwordx4 v[16:17], v[12:15], off offset:576
	v_cvt_pk_bf16_f32 v22, v12, v13
	v_cvt_pk_bf16_f32 v23, v14, v15
	v_mul_f32_e32 v13, v13, v13
	v_fmac_f32_e32 v13, v12, v12
	v_mul_f32_e32 v12, v15, v15
	v_fmac_f32_e32 v12, v14, v14
	v_and_b32_e32 v14, 64, v197
	v_add_f32_e32 v12, v13, v12
	v_xor_b32_e32 v13, 16, v197
	v_add_u32_e32 v14, 64, v14
	v_cmp_lt_i32_e32 vcc, v13, v14
	v_add_f32_e32 v12, v24, v12
	global_store_dwordx2 v[20:21], v[22:23], off offset:288
	v_cndmask_b32_e32 v13, v197, v13, vcc
	v_lshlrev_b32_e32 v13, 2, v13
	ds_bpermute_b32 v13, v13, v12
	s_waitcnt lgkmcnt(0)
	v_add_f32_e32 v12, v12, v13
	v_xor_b32_e32 v13, 32, v197
	v_cmp_lt_i32_e32 vcc, v13, v14
	s_nop 1
	v_cndmask_b32_e32 v13, v197, v13, vcc
	v_lshlrev_b32_e32 v13, 2, v13
	ds_bpermute_b32 v13, v13, v12
	s_and_saveexec_b64 s[38:39], s[0:1]
	s_cbranch_execz .LBB0_1723
	v_lshlrev_b64 v[14:15], 6, v[18:19]
	v_readlane_b32 s26, v254, 43
	v_lshl_add_u64 v[14:15], s[30:31], 0, v[14:15]
	v_readlane_b32 s27, v254, 44
	v_lshl_add_u64 v[14:15], s[50:51], 2, v[14:15]
	s_mov_b32 s29, s27
	s_lshl_b32 s28, s65, 2
	v_writelane_b32 v254, s26, 43
	v_lshl_add_u64 v[14:15], v[14:15], 0, s[28:29]
	s_waitcnt lgkmcnt(0)
	v_add_f32_e32 v12, v12, v13
	v_writelane_b32 v254, s27, 44
	global_store_dword v[14:15], v12, off

.LBB0_1724:
	s_waitcnt lgkmcnt(0)
	s_waitcnt vmcnt(8)
	v_pk_add_f32 v[10:11], v[10:11], v[186:187]
	v_pk_add_f32 v[8:9], v[8:9], v[184:185]
	global_store_dwordx4 v[16:17], v[8:11], off offset:64
	s_waitcnt vmcnt(8)
	v_pk_add_f32 v[6:7], v[6:7], v[190:191]
	v_pk_add_f32 v[4:5], v[4:5], v[188:189]
	global_store_dwordx4 v[16:17], v[4:7], off offset:512
	s_waitcnt vmcnt(8)
	v_pk_add_f32 v[2:3], v[2:3], v[228:229]
	v_pk_add_f32 v[0:1], v[0:1], v[226:227]
	global_store_dwordx4 v[16:17], v[0:3], off offset:576
